# v23 with s_setprio 3 (instead of 1) for waves 4-7 in the attention query-subtile loops
# baseline (speedup 1.0000x reference)
; #define LBAR() do { asm volatile("s_waitcnt lgkmcnt(0)" ::: "memory"); __builtin_amdgcn_s_barrier(); asm volatile("" ::: "memory"); } while (0)
; __device__ __forceinline__ void attn_unit(const AtArgs& A, unsigned char* lds, int unit, int tid, int wave, int lane) {
;     ...
;     for (int rep = 0; rep < 4; ++rep) {
;         const int task = tid + rep * 512, key = task >> 3, c8 = task & 7;
;         const int s = (nb - 1) * 128 + key; const bool valid = s >= 0;
;         const size_t t = (size_t)b * SEQ + (valid ? s : 0);
;         u32x4 w = (u32x4){0, 0, 0, 0};
;         if (valid) w = *(const u32x4*)(Q + t * QW + QC_V + kvh * 64 + c8 * 8);
;         const unsigned ww[4] = {w.x, w.y, w.z, w.w};
;         const int pkey = (((key >> 3) ^ c8) << 3) | (key & 7);
; #pragma unroll
;         for (int i = 0; i < 4; ++i) { VT[(c8 * 8 + 2 * i) * VST + pkey] = (bf16)(ww[i] & 0xffffu); VT[(c8 * 8 + 2 * i + 1) * VST + pkey] = (bf16)(ww[i] >> 16); }
;     }
;     *(u32x4*)(VT + (tid >> 3) * VST + (32 + (tid & 7)) * 8) = (u32x4){0u, 0u, 0u, 0u};
;     LBAR();
;     const int g = wave >> 1, qh = wave & 1, hq = kvh * 4 + g;
;     const float sink = A.sinks[hq];
; #pragma unroll 1
.LBB0_509:
	s_or_b64 exec, exec, s[16:17]
	s_waitcnt vmcnt(0)
	ds_write_b16 v72, v0 offset:36864
	ds_write_b16_d16_hi v73, v0 offset:37552
	ds_write_b16 v72, v1 offset:38240
	ds_write_b16_d16_hi v73, v1 offset:38928
	ds_write_b16 v72, v2 offset:39616
	ds_write_b16_d16_hi v73, v2 offset:40304
	ds_write_b16 v72, v3 offset:40992
	ds_write_b16_d16_hi v73, v3 offset:41680
	ds_write_b128 v74, v[104:107] offset:37376
	s_lshl_b32 s6, s10, 2
	v_readlane_b32 s44, v242, 1
	s_waitcnt lgkmcnt(0)
	s_barrier
	v_mov_b32_e32 v0, s6
	v_readlane_b32 s54, v242, 11
	v_readlane_b32 s55, v242, 12
	s_lshr_b32 s6, s24, 5
	s_and_b32 s6, s6, 1
	s_lshl_b32 s6, s6, 8
	s_and_b32 s12, s35, 31
	s_add_i32 s6, s15, s6
	global_load_dword v38, v0, s[54:55]
	s_lshl_b32 s18, s12, 17
	s_lshl_b64 s[10:11], s[6:7], 1
	s_lshl_b32 s6, s12, 7
	s_cmp_lg_u32 s3, 0
	s_cselect_b64 s[16:17], -1, 0
	s_lshl_b64 s[12:13], s[20:21], 22
	s_or_b32 s3, s12, s18
	s_add_u32 s10, s3, s10
	s_addc_u32 s11, s13, s11
	s_add_u32 s0, s6, s0
	s_addc_u32 s1, 0, s1
	v_lshl_add_u64 v[0:1], s[0:1], 0, v[48:49]
	v_lshlrev_b64 v[0:1], 6, v[0:1]
	v_lshl_add_u64 v[52:53], v[46:47], 0, s[10:11]
	v_lshl_add_u64 v[54:55], s[8:9], 0, v[0:1]
	s_mov_b32 s3, 0xb000
	s_mov_b64 s[20:21], 0
	v_mov_b32_e32 v94, v87
	v_mov_b32_e32 v95, v86
	v_readlane_b32 s45, v242, 2
	v_readlane_b32 s46, v242, 3
	v_readlane_b32 s47, v242, 4
	v_readlane_b32 s48, v242, 5
	v_readlane_b32 s49, v242, 6
	v_readlane_b32 s50, v242, 7
	v_readlane_b32 s51, v242, 8
	v_readlane_b32 s52, v242, 9
	v_readlane_b32 s53, v242, 10
	v_readlane_b32 s56, v242, 13
	v_readlane_b32 s57, v242, 14
	v_readlane_b32 s58, v242, 15
	v_readlane_b32 s59, v242, 16
	v_readlane_b32 s98, v242, 17
	s_cmp_lt_u32 s98, 4
	s_cbranch_scc1 .Lattn_noprio
	s_setprio 3
